# v9 + stack: in-proj relaxed waits, hoisted first LDS reads, attention Q/gate loads de-serialised, GEMM prologue K-tile-1 loads before first wait
# speedup vs baseline: 1.0094x; 1.0094x over previous
; #define PG8_STAGE(bufoff, gbase, voff) do { _Pragma("unroll") for (int _i = 0; _i < 2; ++_i) \
;         __builtin_amdgcn_global_load_lds((const unsigned*)((const char*)(gbase) + (voff)[_i]), (PG8_LAS unsigned*)(lds + (bufoff) + ldsw + _i * 8192), 16, 0, 0); } while (0)
; #define PG8_WAIT_V(n) asm volatile("s_waitcnt vmcnt(" #n ")" ::: "memory")
; #define PG8_BAR __builtin_amdgcn_s_barrier()
; template <class Epi, class Sched, bool ALIGN_EPI = false, bool SP2 = false>
; __device__ __forceinline__ void gemm_phase(PG8_LAS unsigned char* lds, const Gemm g, const Sched& S, const Epi& E) {
;     ...
;     for (int i = 0; i < 2; ++i) { int R, C; stage_rc(tid * 16 + i * 8192, R, C); const int Rb = Epi::PERM ? ((R & ~31) + perm32(R & 31)) : R;
;         voffA[i] = (unsigned)(R * K + C) * 2u; voffB[i] = (unsigned)(Rb * K + C) * 2u; }
;     const size_t kstep = (size_t)(BK * 2);
;     const size_t hstep = (size_t)HALF * K * 2;
;     const size_t tstep = 2 * hstep;
;     const unsigned ldsw = (unsigned)wid * 1024u;
;     const int aoff = lds_byte(wr * 64 + fr, fq * 8), boff = lds_byte(wc * 32 + fr, fq * 8);
;     ...
;     if constexpr (SP2) {
;         PG8_STAGE(PG8_SB(0, 0), cB, voffB); PG8_STAGE(PG8_SB(0, 1), cB + hstep, voffB); PG8_STAGE(PG8_SA(0, 0), cA, voffA); PG8_STAGE(PG8_SA(0, 1), cA + hstep, voffA);
;         if (wr == 1) PG8_BAR;
;         PG8_WAIT_V(2); PG8_BAR;
;         PG8_STAGE(PG8_SB(1, 0), cB + kstep, voffB); PG8_STAGE(PG8_SA(1, 0), cA + kstep, voffA); PG8_STAGE(PG8_SB(1, 1), cB + hstep + kstep, voffB);
;         PG8_WAIT_V(6); PG8_BAR;
.LBB0_552:
	s_and_b64 s[8:9], s[44:45], exec
	s_movk_i32 s8, 0xc00
	s_cselect_b32 s44, s8, 0x1000
	s_cselect_b32 s45, 12, 16
	s_cselect_b32 s54, 0, 8
	s_and_b32 s7, s7, 3
	s_add_i32 m0, s50, 0x18000
	v_lshl_add_u64 v[8:9], v[8:9], 0, s[38:39]
	s_lshl_b32 s10, s6, 13
	s_lshl_b32 s11, s7, 12
	global_load_lds_dwordx4 v[8:9], off
	v_lshl_add_u64 v[6:7], v[6:7], 0, s[38:39]
	s_add_i32 m0, s50, 0x1a000
	s_add_i32 s55, s50, 0x8000
	s_add_i32 s56, s50, 0xa000
	global_load_lds_dwordx4 v[6:7], off
	v_lshl_add_u64 v[2:3], v[2:3], 0, s[38:39]
	s_mov_b32 m0, s55
	s_add_u32 s8, s24, 0x40080
	global_load_lds_dwordx4 v[2:3], off
	v_lshl_add_u64 v[2:3], v[4:5], 0, s[38:39]
	s_mov_b32 m0, s56
	s_addc_u32 s9, s25, 0
	global_load_lds_dwordx4 v[2:3], off
	s_add_i32 m0, s50, 0x1c000
	v_lshl_add_u64 v[2:3], s[8:9], 0, v[158:159]
	global_load_lds_dwordx4 v[2:3], off
	v_lshl_add_u64 v[2:3], s[8:9], 0, v[154:155]
	s_add_i32 m0, s50, 0x1e000
	v_bfe_u32 v4, v0, 4, 2
	global_load_lds_dwordx4 v[2:3], off
	s_waitcnt vmcnt(8)
	s_barrier
	v_and_b32_e32 v3, 15, v0
	v_lshlrev_b32_e32 v5, 4, v4
	v_lshlrev_b32_e32 v0, 2, v0
	v_lshl_or_b32 v174, s6, 6, v3
	v_lshl_or_b32 v3, v3, 6, v5
	v_and_b32_e32 v0, 32, v0
	v_bitop3_b32 v5, v3, s10, v0 bitop3:0xde
	v_bitop3_b32 v175, v3, s11, v0 bitop3:0xde
	v_lshlrev_b32_e32 v3, 14, v14
	v_and_b32_e32 v3, 0xffff8000, v3
	s_sext_i32_i16 s59, s4
	v_lshlrev_b32_e32 v2, 3, v4
	s_cmpk_lt_u32 s5, 0x100
	v_cmp_lt_u32_e64 s[4:5], 1, v4
	v_lshlrev_b32_e32 v0, 5, v4
	v_lshl_add_u32 v3, v13, 11, v3
	v_and_b32_e32 v4, 1, v14
	v_lshl_or_b32 v3, v4, 6, v3
	v_lshl_add_u32 v164, v15, 1, v3
	v_lshlrev_b32_e32 v3, 14, v10
	v_readlane_b32 s12, v253, 40
	v_and_b32_e32 v3, 0xffff8000, v3
	s_waitcnt vmcnt(6)
	v_readlane_b32 s13, v253, 41
	v_lshl_add_u32 v3, v11, 11, v3
	v_and_b32_e32 v4, 1, v10
	s_cselect_b64 s[8:9], -1, 0
	s_cmp_lg_u32 s7, 0
	v_lshl_add_u64 v[162:163], s[12:13], 0, v[0:1]
	v_lshl_or_b32 v0, s7, 5, v2
	v_lshl_or_b32 v3, v4, 6, v3
	s_mov_b32 s57, 0
	s_cselect_b64 s[10:11], -1, 0
	s_lshr_b32 s58, s54, 1
	v_lshl_or_b32 v176, s7, 6, v2
	v_mov_b32_e32 v165, v1
	v_lshl_add_u32 v166, v12, 1, v3
	v_mov_b32_e32 v167, v1
	v_add_u32_e32 v177, 0, v5
	v_lshlrev_b32_e32 v178, 1, v0
	v_lshlrev_b32_e32 v179, 2, v2
	s_barrier
	s_waitcnt vmcnt(0)
	s_branch .LBB0_555
